# v20 + phase C q/q_idx GEMM (K=512, hipcc-unrolled) ported to the LDS-DMA loop
# baseline (speedup 1.0000x reference)
.LBB0_457:
	s_or_b64 exec, exec, s[20:21]
	s_lshl_b32 s6, s33, 10
	s_add_u32 s56, s88, s6
	s_addc_u32 s57, s89, 0
	s_add_u32 s56, s56, 0x7f80000
	s_addc_u32 s57, s57, 0
	s_ashr_i32 s20, s31, 6
	s_ashr_i32 s21, s20, 31
	s_lshl_b64 s[34:35], s[20:21], 17
	s_add_u32 s58, s88, s34
	s_addc_u32 s59, s89, s35
	s_add_u32 s58, s58, 0x2080000
	s_addc_u32 s59, s59, 0
	s_cmp_lt_i32 s20, 8
	s_cselect_b32 s21, s30, 0x4f80000
	s_add_u32 s21, s88, s21
	s_addc_u32 s34, s89, 0
	s_lshl_b32 s20, s20, 8
	s_and_b32 s20, s20, 0x700
	s_add_u32 s20, s21, s20
	s_addc_u32 s21, s34, 0
	s_mov_b32 s6, 0
	v_mov_b32_e32 v78, v186
	v_readfirstlane_b32 s61, v168
	v_lshrrev_b32_e32 v66, 3, v168
	v_bfe_u32 v67, v168, 4, 3
	v_and_b32_e32 v68, 7, v168
	v_xor_b32_e32 v67, v67, v68
	v_lshlrev_b32_e32 v67, 4, v67
	s_lshr_b32 s61, s61, 6
	s_lshl_b32 s61, s61, 10
	s_movk_i32 s60, 0x400
	v_mul_lo_u32 v66, v66, s60
	v_add_u32_e32 v66, v66, v67
	v_add_u32_e32 v67, 0x8000, v66
	v_add_u32_e32 v68, 0x10000, v66
	v_add_u32_e32 v69, 0x18000, v66
	v_add_u32_e32 v70, v115, v117
	v_add_u32_e32 v74, v116, v117
	v_add_u32_e32 v71, v115, v118
	v_add_u32_e32 v75, v116, v118
	v_add_u32_e32 v72, v115, v119
	v_add_u32_e32 v76, v116, v119
	v_add_u32_e32 v73, v115, v120
	v_add_u32_e32 v77, v116, v120
	v_mov_b32_e32 v0, 0
	v_mov_b32_e32 v1, v0
	v_mov_b32_e32 v2, v0
	v_mov_b32_e32 v3, v0
	v_mov_b32_e32 v4, v0
	v_mov_b32_e32 v5, v0
	v_mov_b32_e32 v6, v0
	v_mov_b32_e32 v7, v0
	v_mov_b32_e32 v8, v0
	v_mov_b32_e32 v9, v0
	v_mov_b32_e32 v10, v0
	v_mov_b32_e32 v11, v0
	v_mov_b32_e32 v12, v0
	v_mov_b32_e32 v13, v0
	v_mov_b32_e32 v14, v0
	v_mov_b32_e32 v15, v0
	v_mov_b32_e32 v16, v0
	v_mov_b32_e32 v17, v0
	v_mov_b32_e32 v18, v0
	v_mov_b32_e32 v19, v0
	v_mov_b32_e32 v20, v0
	v_mov_b32_e32 v21, v0
	v_mov_b32_e32 v22, v0
	v_mov_b32_e32 v23, v0
	v_mov_b32_e32 v24, v0
	v_mov_b32_e32 v25, v0
	v_mov_b32_e32 v26, v0
	v_mov_b32_e32 v27, v0
	v_mov_b32_e32 v28, v0
	v_mov_b32_e32 v29, v0
	v_mov_b32_e32 v30, v0
	v_mov_b32_e32 v31, v0
	v_mov_b32_e32 v32, v0
	v_mov_b32_e32 v33, v0
	v_mov_b32_e32 v34, v0
	v_mov_b32_e32 v35, v0
	v_mov_b32_e32 v36, v0
	v_mov_b32_e32 v37, v0
	v_mov_b32_e32 v38, v0
	v_mov_b32_e32 v39, v0
	v_mov_b32_e32 v40, v0
	v_mov_b32_e32 v41, v0
	v_mov_b32_e32 v42, v0
	v_mov_b32_e32 v43, v0
	v_mov_b32_e32 v44, v0
	v_mov_b32_e32 v45, v0
	v_mov_b32_e32 v46, v0
	v_mov_b32_e32 v47, v0
	v_mov_b32_e32 v48, v0
	v_mov_b32_e32 v49, v0
	v_mov_b32_e32 v50, v0
	v_mov_b32_e32 v51, v0
	v_mov_b32_e32 v52, v0
	v_mov_b32_e32 v53, v0
	v_mov_b32_e32 v54, v0
	v_mov_b32_e32 v55, v0
	v_mov_b32_e32 v56, v0
	v_mov_b32_e32 v57, v0
	v_mov_b32_e32 v58, v0
	v_mov_b32_e32 v59, v0
	v_mov_b32_e32 v60, v0
	v_mov_b32_e32 v61, v0
	v_mov_b32_e32 v62, v0
	v_mov_b32_e32 v63, v0
	s_add_u32 m0, s61, 0x0
	s_nop 0
	global_load_lds_dwordx4 v66, s[56:57]
	s_add_u32 m0, s61, 0x1000
	s_nop 0
	global_load_lds_dwordx4 v67, s[56:57]
	s_add_u32 m0, s61, 0x2000
	s_nop 0
	global_load_lds_dwordx4 v68, s[56:57]
	s_add_u32 m0, s61, 0x3000
	s_nop 0
	global_load_lds_dwordx4 v69, s[56:57]
	s_add_u32 m0, s61, 0x8000
	s_nop 0
	global_load_lds_dwordx4 v66, s[58:59]
	s_add_u32 m0, s61, 0x9000
	s_nop 0
	global_load_lds_dwordx4 v67, s[58:59]
	s_add_u32 m0, s61, 0xa000
	s_nop 0
	global_load_lds_dwordx4 v68, s[58:59]
	s_add_u32 m0, s61, 0xb000
	s_nop 0
	global_load_lds_dwordx4 v69, s[58:59]
	s_add_u32 s56, s56, 0x80
	s_addc_u32 s57, s57, 0
	s_add_u32 s58, s58, 0x80
	s_addc_u32 s59, s59, 0
	s_add_u32 m0, s61, 0x4000
	s_nop 0
	global_load_lds_dwordx4 v66, s[56:57]
	s_add_u32 m0, s61, 0x5000
	s_nop 0
	global_load_lds_dwordx4 v67, s[56:57]
	s_add_u32 m0, s61, 0x6000
	s_nop 0
	global_load_lds_dwordx4 v68, s[56:57]
	s_add_u32 m0, s61, 0x7000
	s_nop 0
	global_load_lds_dwordx4 v69, s[56:57]
	s_add_u32 m0, s61, 0xc000
	s_nop 0
	global_load_lds_dwordx4 v66, s[58:59]
	s_add_u32 m0, s61, 0xd000
	s_nop 0
	global_load_lds_dwordx4 v67, s[58:59]
	s_add_u32 m0, s61, 0xe000
	s_nop 0
	global_load_lds_dwordx4 v68, s[58:59]
	s_add_u32 m0, s61, 0xf000
	s_nop 0
	global_load_lds_dwordx4 v69, s[58:59]
	s_add_u32 s56, s56, 0x80
	s_addc_u32 s57, s57, 0
	s_add_u32 s58, s58, 0x80
	s_addc_u32 s59, s59, 0
	s_waitcnt vmcnt(8)
	s_barrier
	ds_read_b128 v[186:189], v70 offset:0
	ds_read_b128 v[190:193], v70 offset:4096
	ds_read_b128 v[194:197], v74 offset:32768
	ds_read_b128 v[198:201], v74 offset:36864
	ds_read_b128 v[202:205], v71 offset:0
	ds_read_b128 v[206:209], v71 offset:4096
	ds_read_b128 v[210:213], v75 offset:32768
	ds_read_b128 v[214:217], v75 offset:36864
	ds_read_b128 v[218:221], v72 offset:0
	ds_read_b128 v[222:225], v72 offset:4096
	ds_read_b128 v[226:229], v76 offset:32768
	ds_read_b128 v[230:233], v76 offset:36864
	s_mov_b32 s60, 0
.Lgm_loop_gemmC2:
	ds_read_b128 v[234:237], v73 offset:0
	ds_read_b128 v[238:241], v73 offset:4096
	ds_read_b128 v[242:245], v77 offset:32768
	ds_read_b128 v[246:249], v77 offset:36864
	s_waitcnt lgkmcnt(12)
	v_mfma_f32_32x32x16_bf16 v[0:15], v[186:189], v[194:197], v[0:15]
	v_mfma_f32_32x32x16_bf16 v[16:31], v[186:189], v[198:201], v[16:31]
	v_mfma_f32_32x32x16_bf16 v[32:47], v[190:193], v[194:197], v[32:47]
	v_mfma_f32_32x32x16_bf16 v[48:63], v[190:193], v[198:201], v[48:63]
	s_waitcnt vmcnt(0) lgkmcnt(0)
	s_barrier
	s_cmp_lt_u32 s60, 6
	s_cbranch_scc0 .Lgm_nodma0_gemmC2
	ds_read_b128 v[186:189], v70 offset:16384
	s_add_u32 m0, s61, 0x0
	s_nop 0
	global_load_lds_dwordx4 v66, s[56:57]
	v_mfma_f32_32x32x16_bf16 v[0:15], v[202:205], v[210:213], v[0:15]
	ds_read_b128 v[190:193], v70 offset:20480
	s_add_u32 m0, s61, 0x1000
	s_nop 0
	global_load_lds_dwordx4 v67, s[56:57]
	v_mfma_f32_32x32x16_bf16 v[16:31], v[202:205], v[214:217], v[16:31]
	ds_read_b128 v[194:197], v74 offset:49152
	s_add_u32 m0, s61, 0x2000
	s_nop 0
	global_load_lds_dwordx4 v68, s[56:57]
	v_mfma_f32_32x32x16_bf16 v[32:47], v[206:209], v[210:213], v[32:47]
	ds_read_b128 v[198:201], v74 offset:53248
	s_add_u32 m0, s61, 0x3000
	s_nop 0
	global_load_lds_dwordx4 v69, s[56:57]
	v_mfma_f32_32x32x16_bf16 v[48:63], v[206:209], v[214:217], v[48:63]
	ds_read_b128 v[202:205], v71 offset:16384
	s_add_u32 m0, s61, 0x8000
	s_nop 0
	global_load_lds_dwordx4 v66, s[58:59]
	v_mfma_f32_32x32x16_bf16 v[0:15], v[218:221], v[226:229], v[0:15]
	ds_read_b128 v[206:209], v71 offset:20480
	s_add_u32 m0, s61, 0x9000
	s_nop 0
	global_load_lds_dwordx4 v67, s[58:59]
	v_mfma_f32_32x32x16_bf16 v[16:31], v[218:221], v[230:233], v[16:31]
	ds_read_b128 v[210:213], v75 offset:49152
	s_add_u32 m0, s61, 0xa000
	s_nop 0
	global_load_lds_dwordx4 v68, s[58:59]
	v_mfma_f32_32x32x16_bf16 v[32:47], v[222:225], v[226:229], v[32:47]
	ds_read_b128 v[214:217], v75 offset:53248
	s_add_u32 m0, s61, 0xb000
	s_nop 0
	global_load_lds_dwordx4 v69, s[58:59]
	v_mfma_f32_32x32x16_bf16 v[48:63], v[222:225], v[230:233], v[48:63]
	ds_read_b128 v[218:221], v72 offset:16384
	s_add_u32 s56, s56, 0x80
	s_addc_u32 s57, s57, 0
	s_add_u32 s58, s58, 0x80
	s_addc_u32 s59, s59, 0
	v_mfma_f32_32x32x16_bf16 v[0:15], v[234:237], v[242:245], v[0:15]
	ds_read_b128 v[222:225], v72 offset:20480
	v_mfma_f32_32x32x16_bf16 v[16:31], v[234:237], v[246:249], v[16:31]
	ds_read_b128 v[226:229], v76 offset:49152
	v_mfma_f32_32x32x16_bf16 v[32:47], v[238:241], v[242:245], v[32:47]
	ds_read_b128 v[230:233], v76 offset:53248
	v_mfma_f32_32x32x16_bf16 v[48:63], v[238:241], v[246:249], v[48:63]
	s_branch .Lgm_join0_gemmC2
.Lgm_nodma0_gemmC2:
	ds_read_b128 v[186:189], v70 offset:16384
	v_mfma_f32_32x32x16_bf16 v[0:15], v[202:205], v[210:213], v[0:15]
	ds_read_b128 v[190:193], v70 offset:20480
	v_mfma_f32_32x32x16_bf16 v[16:31], v[202:205], v[214:217], v[16:31]
	ds_read_b128 v[194:197], v74 offset:49152
	v_mfma_f32_32x32x16_bf16 v[32:47], v[206:209], v[210:213], v[32:47]
	ds_read_b128 v[198:201], v74 offset:53248
	v_mfma_f32_32x32x16_bf16 v[48:63], v[206:209], v[214:217], v[48:63]
	ds_read_b128 v[202:205], v71 offset:16384
	v_mfma_f32_32x32x16_bf16 v[0:15], v[218:221], v[226:229], v[0:15]
	ds_read_b128 v[206:209], v71 offset:20480
	v_mfma_f32_32x32x16_bf16 v[16:31], v[218:221], v[230:233], v[16:31]
	ds_read_b128 v[210:213], v75 offset:49152
	v_mfma_f32_32x32x16_bf16 v[32:47], v[222:225], v[226:229], v[32:47]
	ds_read_b128 v[214:217], v75 offset:53248
	v_mfma_f32_32x32x16_bf16 v[48:63], v[222:225], v[230:233], v[48:63]
	ds_read_b128 v[218:221], v72 offset:16384
	v_mfma_f32_32x32x16_bf16 v[0:15], v[234:237], v[242:245], v[0:15]
	ds_read_b128 v[222:225], v72 offset:20480
	v_mfma_f32_32x32x16_bf16 v[16:31], v[234:237], v[246:249], v[16:31]
	ds_read_b128 v[226:229], v76 offset:49152
	v_mfma_f32_32x32x16_bf16 v[32:47], v[238:241], v[242:245], v[32:47]
	ds_read_b128 v[230:233], v76 offset:53248
	v_mfma_f32_32x32x16_bf16 v[48:63], v[238:241], v[246:249], v[48:63]
.Lgm_join0_gemmC2:
	ds_read_b128 v[234:237], v73 offset:16384
	ds_read_b128 v[238:241], v73 offset:20480
	ds_read_b128 v[242:245], v77 offset:49152
	ds_read_b128 v[246:249], v77 offset:53248
	s_waitcnt lgkmcnt(12)
	v_mfma_f32_32x32x16_bf16 v[0:15], v[186:189], v[194:197], v[0:15]
	v_mfma_f32_32x32x16_bf16 v[16:31], v[186:189], v[198:201], v[16:31]
	v_mfma_f32_32x32x16_bf16 v[32:47], v[190:193], v[194:197], v[32:47]
	v_mfma_f32_32x32x16_bf16 v[48:63], v[190:193], v[198:201], v[48:63]
	s_waitcnt vmcnt(0) lgkmcnt(0)
	s_barrier
	s_cmp_lt_u32 s60, 6
	s_cbranch_scc0 .Lgm_nodma1_gemmC2
	ds_read_b128 v[186:189], v70 offset:0
	s_add_u32 m0, s61, 0x4000
	s_nop 0
	global_load_lds_dwordx4 v66, s[56:57]
	v_mfma_f32_32x32x16_bf16 v[0:15], v[202:205], v[210:213], v[0:15]
	ds_read_b128 v[190:193], v70 offset:4096
	s_add_u32 m0, s61, 0x5000
	s_nop 0
	global_load_lds_dwordx4 v67, s[56:57]
	v_mfma_f32_32x32x16_bf16 v[16:31], v[202:205], v[214:217], v[16:31]
	ds_read_b128 v[194:197], v74 offset:32768
	s_add_u32 m0, s61, 0x6000
	s_nop 0
	global_load_lds_dwordx4 v68, s[56:57]
	v_mfma_f32_32x32x16_bf16 v[32:47], v[206:209], v[210:213], v[32:47]
	ds_read_b128 v[198:201], v74 offset:36864
	s_add_u32 m0, s61, 0x7000
	s_nop 0
	global_load_lds_dwordx4 v69, s[56:57]
	v_mfma_f32_32x32x16_bf16 v[48:63], v[206:209], v[214:217], v[48:63]
	ds_read_b128 v[202:205], v71 offset:0
	s_add_u32 m0, s61, 0xc000
	s_nop 0
	global_load_lds_dwordx4 v66, s[58:59]
	v_mfma_f32_32x32x16_bf16 v[0:15], v[218:221], v[226:229], v[0:15]
	ds_read_b128 v[206:209], v71 offset:4096
	s_add_u32 m0, s61, 0xd000
	s_nop 0
	global_load_lds_dwordx4 v67, s[58:59]
	v_mfma_f32_32x32x16_bf16 v[16:31], v[218:221], v[230:233], v[16:31]
	ds_read_b128 v[210:213], v75 offset:32768
	s_add_u32 m0, s61, 0xe000
	s_nop 0
	global_load_lds_dwordx4 v68, s[58:59]
	v_mfma_f32_32x32x16_bf16 v[32:47], v[222:225], v[226:229], v[32:47]
	ds_read_b128 v[214:217], v75 offset:36864
	s_add_u32 m0, s61, 0xf000
	s_nop 0
	global_load_lds_dwordx4 v69, s[58:59]
	v_mfma_f32_32x32x16_bf16 v[48:63], v[222:225], v[230:233], v[48:63]
	ds_read_b128 v[218:221], v72 offset:0
	s_add_u32 s56, s56, 0x80
	s_addc_u32 s57, s57, 0
	s_add_u32 s58, s58, 0x80
	s_addc_u32 s59, s59, 0
	v_mfma_f32_32x32x16_bf16 v[0:15], v[234:237], v[242:245], v[0:15]
	ds_read_b128 v[222:225], v72 offset:4096
	v_mfma_f32_32x32x16_bf16 v[16:31], v[234:237], v[246:249], v[16:31]
	ds_read_b128 v[226:229], v76 offset:32768
	v_mfma_f32_32x32x16_bf16 v[32:47], v[238:241], v[242:245], v[32:47]
	ds_read_b128 v[230:233], v76 offset:36864
	v_mfma_f32_32x32x16_bf16 v[48:63], v[238:241], v[246:249], v[48:63]
	s_branch .Lgm_join1_gemmC2
.Lgm_nodma1_gemmC2:
	ds_read_b128 v[186:189], v70 offset:0
	v_mfma_f32_32x32x16_bf16 v[0:15], v[202:205], v[210:213], v[0:15]
	ds_read_b128 v[190:193], v70 offset:4096
	v_mfma_f32_32x32x16_bf16 v[16:31], v[202:205], v[214:217], v[16:31]
	ds_read_b128 v[194:197], v74 offset:32768
	v_mfma_f32_32x32x16_bf16 v[32:47], v[206:209], v[210:213], v[32:47]
	ds_read_b128 v[198:201], v74 offset:36864
	v_mfma_f32_32x32x16_bf16 v[48:63], v[206:209], v[214:217], v[48:63]
	ds_read_b128 v[202:205], v71 offset:0
	v_mfma_f32_32x32x16_bf16 v[0:15], v[218:221], v[226:229], v[0:15]
	ds_read_b128 v[206:209], v71 offset:4096
	v_mfma_f32_32x32x16_bf16 v[16:31], v[218:221], v[230:233], v[16:31]
	ds_read_b128 v[210:213], v75 offset:32768
	v_mfma_f32_32x32x16_bf16 v[32:47], v[222:225], v[226:229], v[32:47]
	ds_read_b128 v[214:217], v75 offset:36864
	v_mfma_f32_32x32x16_bf16 v[48:63], v[222:225], v[230:233], v[48:63]
	ds_read_b128 v[218:221], v72 offset:0
	v_mfma_f32_32x32x16_bf16 v[0:15], v[234:237], v[242:245], v[0:15]
	ds_read_b128 v[222:225], v72 offset:4096
	v_mfma_f32_32x32x16_bf16 v[16:31], v[234:237], v[246:249], v[16:31]
	ds_read_b128 v[226:229], v76 offset:32768
	v_mfma_f32_32x32x16_bf16 v[32:47], v[238:241], v[242:245], v[32:47]
	ds_read_b128 v[230:233], v76 offset:36864
	v_mfma_f32_32x32x16_bf16 v[48:63], v[238:241], v[246:249], v[48:63]
.Lgm_join1_gemmC2:
	s_add_u32 s60, s60, 2
	s_cmp_lt_u32 s60, 8
	s_cbranch_scc1 .Lgm_loop_gemmC2
	s_waitcnt lgkmcnt(0)
	s_barrier
	s_nop 7
	v_mov_b32_e32 v186, v78
	v_mov_b32_e32 v99, v85
	v_lshl_add_u64 v[64:65], s[20:21], 0, v[98:99]
	s_mov_b64 s[20:21], -1
